# attention: fill the 12 post-QK-MFMA wait states with the V-fragment ds_reads instead of s_nop 11
# speedup vs baseline: 1.0055x; 1.0055x over previous
; #define MFMA(a, b, c) __builtin_amdgcn_mfma_f32_32x32x16_bf16((a), (b), (c), 0, 0, 0)
; DI float fexp2(float x) { return __builtin_amdgcn_exp2f(x); }
; DI f32x16 zero16() { f32x16 z; for (int i = 0; i < 16; ++i) z[i] = 0.f; return z; }
; DI void phase_attn(const Params& p, int hf, bool skipctx, char* smem, int& rot) {
;     ...
;     auto compute = [&](int buf, int half) {
;       const char* sk = smem + buf * STG + half * 64 * KROW; const char* sv = smem + buf * STG + KB_ + half * 128;
;       f32x16 st[2]; st[0] = zero16(); st[1] = zero16();
;       {
;         bf16x8 kf[2][6];
; #pragma unroll
;         for (int kb = 0; kb < 2; ++kb)
; #pragma unroll
;           for (int ks = 0; ks < 6; ++ks) kf[kb][ks] = *(const bf16x8*)(sk + (kb * 32 + r) * KROW + (ks * 16 + h * 8) * 2);
;         __builtin_amdgcn_sched_barrier(0);
; #pragma unroll
;         for (int ks = 0; ks < 6; ++ks)
; #pragma unroll
;           for (int kb = 0; kb < 2; ++kb) st[kb] = MFMA(kf[kb][ks], qf[ks], st[kb]);
;         __builtin_amdgcn_sched_barrier(0);
;       }
;       bf16x8 vf[2][2][2];
; #pragma unroll
;       for (int kb = 0; kb < 2; ++kb)
; #pragma unroll
;         for (int s2 = 0; s2 < 2; ++s2)
; #pragma unroll
;           for (int dvb = 0; dvb < 2; ++dvb) {
;             const char* vp = sv + (dvb * 32 + r) * VROW + (kb * 32 + 16 * s2 + 4 * h) * 2;
;             const s16x4 lo = *(const s16x4*)vp, hi = *(const s16x4*)(vp + 16);
;             vf[kb][s2][dvb] = __builtin_shufflevector(lo, hi, 0, 1, 2, 3, 4, 5, 6, 7);
;           }
;       float mx = st[0][0];
; #pragma unroll
;       for (int i = 0; i < 16; ++i) { mx = fmaxf(mx, st[0][i]); mx = fmaxf(mx, st[1][i]); }
;       if (__any(mx > m_run + 8.f)) {
;         mx = fmaxf(mx, __shfl_xor(mx, 32));
;         const float m_new = fmaxf(m_run, mx);
;         const float alpha = fexp2(m_run - m_new);
;         m_run = m_new;
;         l_run *= alpha;
; #pragma unroll
;         for (int i = 0; i < 16; ++i) { o[0][i] *= alpha; o[1][i] *= alpha; }
;       }
.LBB0_797:
	ds_read_b128 v[32:35], v190
	ds_read_b128 v[128:131], v190 offset:32
	ds_read_b128 v[132:135], v190 offset:64
	ds_read_b128 v[136:139], v190 offset:96
	ds_read_b128 v[140:143], v190 offset:128
	ds_read_b128 v[144:147], v190 offset:160
	ds_read_b128 v[36:39], v190 offset:6656
	ds_read_b128 v[148:151], v190 offset:6688
	ds_read_b128 v[152:155], v190 offset:6720
	ds_read_b128 v[156:159], v190 offset:6752
	ds_read_b128 v[214:217], v190 offset:6784
	ds_read_b128 v[234:237], v190 offset:6816
	s_waitcnt lgkmcnt(11)
	v_mfma_f32_32x32x16_bf16 v[48:63], v[32:35], v[64:67], 0
	s_waitcnt lgkmcnt(5)
	v_mfma_f32_32x32x16_bf16 v[32:47], v[36:39], v[64:67], 0
	v_mfma_f32_32x32x16_bf16 v[48:63], v[128:131], v[68:71], v[48:63]
	s_waitcnt lgkmcnt(4)
	v_mfma_f32_32x32x16_bf16 v[32:47], v[148:151], v[68:71], v[32:47]
	v_mfma_f32_32x32x16_bf16 v[48:63], v[132:135], v[72:75], v[48:63]
	s_waitcnt lgkmcnt(3)
	v_mfma_f32_32x32x16_bf16 v[32:47], v[152:155], v[72:75], v[32:47]
	v_mfma_f32_32x32x16_bf16 v[48:63], v[136:139], v[88:91], v[48:63]
	s_waitcnt lgkmcnt(2)
	v_mfma_f32_32x32x16_bf16 v[32:47], v[156:159], v[88:91], v[32:47]
	v_mfma_f32_32x32x16_bf16 v[48:63], v[140:143], v[96:99], v[48:63]
	s_waitcnt lgkmcnt(1)
	v_mfma_f32_32x32x16_bf16 v[32:47], v[214:217], v[96:99], v[32:47]
	v_mfma_f32_32x32x16_bf16 v[48:63], v[144:147], v[100:103], v[48:63]
	s_waitcnt lgkmcnt(0)
	v_mfma_f32_32x32x16_bf16 v[32:47], v[234:237], v[100:103], v[32:47]
	s_nop 1
	v_add_u32_e32 v214, 0x6800, v191
	v_add_u32_e32 v215, 0x8800, v191
	ds_read2_b64 v[156:159], v214 offset1:2
	ds_read2_b64 v[148:151], v214 offset0:4 offset1:6
	ds_read2_b64 v[152:155], v215 offset0:32 offset1:34
	ds_read2_b64 v[144:147], v215 offset0:36 offset1:38
	ds_read2_b64 v[140:143], v214 offset0:8 offset1:10
	ds_read2_b64 v[136:139], v215 offset0:40 offset1:42
	ds_read2_b64 v[132:135], v214 offset0:12 offset1:14
	ds_read2_b64 v[128:131], v215 offset0:44 offset1:46
	v_max_f32_e32 v195, v32, v32
	v_max_f32_e32 v200, v48, v48
	v_max_f32_e32 v195, v200, v195
	v_max3_f32 v195, v195, v49, v33
	v_max3_f32 v195, v195, v50, v34
	v_max3_f32 v195, v195, v51, v35
	v_max3_f32 v195, v195, v52, v36
	v_max3_f32 v195, v195, v53, v37
	v_max3_f32 v195, v195, v54, v38
	v_max3_f32 v195, v195, v55, v39
	v_max3_f32 v195, v195, v56, v40
	v_max3_f32 v195, v195, v57, v41
	v_max3_f32 v195, v195, v58, v42
	v_max3_f32 v195, v195, v59, v43
	v_max3_f32 v195, v195, v60, v44
	v_max3_f32 v195, v195, v61, v45
	v_max3_f32 v195, v195, v62, v46
	v_max3_f32 v217, v195, v63, v47
	v_add_f32_e32 v216, 0x41000000, v212
	v_cmp_gt_f32_e32 vcc, v217, v216
	s_cbranch_vccz .LBB0_799
	v_cmp_lt_i32_e32 vcc, v224, v207
	s_nop 1
	v_cndmask_b32_e32 v195, v205, v224, vcc
	v_lshlrev_b32_e32 v195, 2, v195
	ds_bpermute_b32 v195, v195, v217
	s_waitcnt lgkmcnt(0)
	v_max3_f32 v195, v212, v217, v195
	v_sub_f32_e32 v200, v212, v195
	v_exp_f32_e32 v200, v200
	v_add_f32_e32 v216, 0x41000000, v195
	v_mov_b32_e32 v212, v195
	v_mul_f32_e32 v213, v213, v200
	v_pk_mul_f32 v[30:31], v[30:31], v[200:201] op_sel_hi:[1,0]
	v_pk_mul_f32 v[28:29], v[28:29], v[200:201] op_sel_hi:[1,0]
	v_pk_mul_f32 v[26:27], v[26:27], v[200:201] op_sel_hi:[1,0]
	v_pk_mul_f32 v[24:25], v[24:25], v[200:201] op_sel_hi:[1,0]
	v_pk_mul_f32 v[22:23], v[22:23], v[200:201] op_sel_hi:[1,0]
	v_pk_mul_f32 v[20:21], v[20:21], v[200:201] op_sel_hi:[1,0]
	v_pk_mul_f32 v[18:19], v[18:19], v[200:201] op_sel_hi:[1,0]
	v_pk_mul_f32 v[16:17], v[16:17], v[200:201] op_sel_hi:[1,0]
	v_pk_mul_f32 v[14:15], v[14:15], v[200:201] op_sel_hi:[1,0]
	v_pk_mul_f32 v[12:13], v[12:13], v[200:201] op_sel_hi:[1,0]
	v_pk_mul_f32 v[10:11], v[10:11], v[200:201] op_sel_hi:[1,0]
	v_pk_mul_f32 v[8:9], v[8:9], v[200:201] op_sel_hi:[1,0]
	v_pk_mul_f32 v[6:7], v[6:7], v[200:201] op_sel_hi:[1,0]
	v_pk_mul_f32 v[4:5], v[4:5], v[200:201] op_sel_hi:[1,0]
	v_pk_mul_f32 v[2:3], v[2:3], v[200:201] op_sel_hi:[1,0]
	v_pk_mul_f32 v[0:1], v[0:1], v[200:201] op_sel_hi:[1,0]
.LBB0_799:
	v_sub_f32_e32 v48, v48, v212
	v_exp_f32_e32 v48, v48
	v_sub_f32_e32 v49, v49, v212
	v_exp_f32_e32 v49, v49
	v_sub_f32_e32 v50, v50, v212
	v_exp_f32_e32 v50, v50
	v_sub_f32_e32 v51, v51, v212
	v_exp_f32_e32 v51, v51
	v_sub_f32_e32 v52, v52, v212
	v_add_f32_e32 v195, 0, v48
	v_exp_f32_e32 v52, v52
	v_sub_f32_e32 v53, v53, v212
	v_add_f32_e32 v195, v49, v195
	v_exp_f32_e32 v53, v53
	v_sub_f32_e32 v54, v54, v212
	v_add_f32_e32 v195, v50, v195
	v_exp_f32_e32 v54, v54
	v_sub_f32_e32 v55, v55, v212
	v_add_f32_e32 v195, v51, v195
	v_exp_f32_e32 v55, v55
	v_sub_f32_e32 v56, v56, v212
	v_add_f32_e32 v195, v52, v195
	v_exp_f32_e32 v56, v56
	v_sub_f32_e32 v57, v57, v212
	v_add_f32_e32 v195, v53, v195
	v_exp_f32_e32 v57, v57
	v_sub_f32_e32 v58, v58, v212
	v_add_f32_e32 v195, v54, v195
	v_exp_f32_e32 v58, v58
	v_sub_f32_e32 v59, v59, v212
	v_add_f32_e32 v195, v55, v195
	v_exp_f32_e32 v59, v59
	v_sub_f32_e32 v60, v60, v212
	v_add_f32_e32 v195, v56, v195
	v_exp_f32_e32 v60, v60
	v_sub_f32_e32 v61, v61, v212
	v_add_f32_e32 v195, v57, v195
	v_exp_f32_e32 v61, v61
	v_sub_f32_e32 v62, v62, v212
	v_add_f32_e32 v195, v58, v195
	v_exp_f32_e32 v62, v62
	v_sub_f32_e32 v63, v63, v212
	v_add_f32_e32 v195, v59, v195
	v_exp_f32_e32 v63, v63
	v_sub_f32_e32 v32, v32, v212
	v_add_f32_e32 v195, v60, v195
	v_exp_f32_e32 v200, v32
	v_sub_f32_e32 v32, v33, v212
	v_add_f32_e32 v195, v61, v195
	v_exp_f32_e32 v201, v32
	v_sub_f32_e32 v33, v34, v212
	v_add_f32_e32 v32, v62, v195
	v_exp_f32_e32 v195, v33
	v_sub_f32_e32 v33, v35, v212
	v_add_f32_e32 v32, v63, v32
	v_exp_f32_e32 v202, v33
	v_sub_f32_e32 v33, v36, v212
	v_add_f32_e32 v32, v200, v32
	v_exp_f32_e32 v36, v33
	v_sub_f32_e32 v33, v37, v212
	v_add_f32_e32 v32, v201, v32
	v_exp_f32_e32 v37, v33
	v_add_f32_e32 v32, v195, v32
	v_add_f32_e32 v32, v202, v32
	v_add_f32_e32 v32, v36, v32
	v_add_f32_e32 v203, v37, v32
	v_cvt_pk_bf16_f32 v32, v48, v49
	v_cvt_pk_bf16_f32 v33, v50, v51
	v_cvt_pk_bf16_f32 v34, v52, v53
	v_cvt_pk_bf16_f32 v35, v54, v55
	v_sub_f32_e32 v38, v38, v212
	v_exp_f32_e32 v38, v38
	s_waitcnt lgkmcnt(7)
; DI float fexp2(float x) { return __builtin_amdgcn_exp2f(x); }
; DI void phase_attn(const Params& p, int hf, bool skipctx, char* smem, int& rot) {
;     ...
;     auto compute = [&](int buf, int half) {
;       const char* sk = smem + buf * STG + half * 64 * KROW; const char* sv = smem + buf * STG + KB_ + half * 128;
;       f32x16 st[2]; st[0] = zero16(); st[1] = zero16();
;       {
;         bf16x8 kf[2][6];
; #pragma unroll
;         for (int kb = 0; kb < 2; ++kb)
; #pragma unroll
;           for (int ks = 0; ks < 6; ++ks) kf[kb][ks] = *(const bf16x8*)(sk + (kb * 32 + r) * KROW + (ks * 16 + h * 8) * 2);
;         __builtin_amdgcn_sched_barrier(0);
; #pragma unroll
;         for (int ks = 0; ks < 6; ++ks)
; #pragma unroll
;           for (int kb = 0; kb < 2; ++kb) st[kb] = MFMA(kf[kb][ks], qf[ks], st[kb]);
;         __builtin_amdgcn_sched_barrier(0);
;       }
;       bf16x8 vf[2][2][2];
; #pragma unroll
;       for (int kb = 0; kb < 2; ++kb)
; #pragma unroll
;         for (int s2 = 0; s2 < 2; ++s2)
; #pragma unroll
;           for (int dvb = 0; dvb < 2; ++dvb) {
;             const char* vp = sv + (dvb * 32 + r) * VROW + (kb * 32 + 16 * s2 + 4 * h) * 2;
;             const s16x4 lo = *(const s16x4*)vp, hi = *(const s16x4*)(vp + 16);
;             vf[kb][s2][dvb] = __builtin_shufflevector(lo, hi, 0, 1, 2, 3, 4, 5, 6, 7);
;           }
;       float mx = st[0][0];
; #pragma unroll
;       for (int i = 0; i < 16; ++i) { mx = fmaxf(mx, st[0][i]); mx = fmaxf(mx, st[1][i]); }
;       if (__any(mx > m_run + 8.f)) {
;         mx = fmaxf(mx, __shfl_xor(mx, 32));
;         const float m_new = fmaxf(m_run, mx);
;         const float alpha = fexp2(m_run - m_new);
;         m_run = m_new;
;         l_run *= alpha;
; #pragma unroll
;         for (int i = 0; i < 16; ++i) { o[0][i] *= alpha; o[1][i] *= alpha; }
;       }
;       float ps = 0.f;
; #pragma unroll
;       for (int kb = 0; kb < 2; ++kb)
; #pragma unroll
;         for (int i = 0; i < 16; ++i) { const float e = fexp2(st[kb][i] - m_run); st[kb][i] = e; ps += e; }
;       l_run += ps;
; #pragma unroll
;       for (int kb = 0; kb < 2; ++kb)
; #pragma unroll
;         for (int s2 = 0; s2 < 2; ++s2) {
;           const bf16x8 pb = pack8(st[kb][8 * s2 + 0], st[kb][8 * s2 + 1], st[kb][8 * s2 + 2], st[kb][8 * s2 + 3], st[kb][8 * s2 + 4], st[kb][8 * s2 + 5], st[kb][8 * s2 + 6], st[kb][8 * s2 + 7]);
; #pragma unroll
	v_mfma_f32_32x32x16_bf16 v[16:31], v[156:159], v[32:35], v[16:31]
	v_sub_f32_e32 v39, v39, v212
	v_exp_f32_e32 v39, v39
	v_sub_f32_e32 v40, v40, v212
	v_exp_f32_e32 v40, v40
	v_sub_f32_e32 v42, v42, v212
	v_add_f32_e32 v48, v38, v203
	v_exp_f32_e32 v42, v42
	s_waitcnt lgkmcnt(5)
	v_mfma_f32_32x32x16_bf16 v[0:15], v[152:155], v[32:35], v[0:15]
	v_sub_f32_e32 v32, v41, v212
	v_exp_f32_e32 v41, v32
	v_cvt_pk_bf16_f32 v32, v56, v57
	v_cvt_pk_bf16_f32 v33, v58, v59
	v_cvt_pk_bf16_f32 v34, v60, v61
	v_cvt_pk_bf16_f32 v35, v62, v63
	v_sub_f32_e32 v43, v43, v212
	v_add_f32_e32 v48, v39, v48
	v_mfma_f32_32x32x16_bf16 v[16:31], v[148:151], v[32:35], v[16:31]
	v_exp_f32_e32 v43, v43
	v_sub_f32_e32 v44, v44, v212
	v_add_f32_e32 v48, v40, v48
	v_exp_f32_e32 v44, v44
	v_add_f32_e32 v48, v41, v48
	s_waitcnt lgkmcnt(4)
	v_mfma_f32_32x32x16_bf16 v[0:15], v[144:147], v[32:35], v[0:15]
	v_add_f32_e32 v32, v42, v48
	v_add_f32_e32 v32, v43, v32
	v_add_f32_e32 v48, v44, v32
	v_cvt_pk_bf16_f32 v32, v200, v201
	v_cvt_pk_bf16_f32 v33, v195, v202
	v_cvt_pk_bf16_f32 v34, v36, v37
	v_cvt_pk_bf16_f32 v35, v38, v39
	v_sub_f32_e32 v36, v45, v212
	v_exp_f32_e32 v36, v36
	s_waitcnt lgkmcnt(3)
	v_mfma_f32_32x32x16_bf16 v[16:31], v[140:143], v[32:35], v[16:31]
	v_sub_f32_e32 v37, v46, v212
	v_exp_f32_e32 v37, v37
	v_sub_f32_e32 v38, v47, v212
	v_exp_f32_e32 v38, v38
	v_add_f32_e32 v39, v36, v48
	s_waitcnt lgkmcnt(2)
	v_mfma_f32_32x32x16_bf16 v[0:15], v[136:139], v[32:35], v[0:15]
	v_add_f32_e32 v32, v37, v39
	v_add_f32_e32 v32, v38, v32
	v_add_f32_e32 v213, v213, v32
	v_cvt_pk_bf16_f32 v32, v40, v41
	v_cvt_pk_bf16_f32 v33, v42, v43
	v_cvt_pk_bf16_f32 v34, v44, v36
	v_cvt_pk_bf16_f32 v35, v37, v38
	s_waitcnt lgkmcnt(1)
	s_nop 0
	v_mfma_f32_32x32x16_bf16 v[16:31], v[132:135], v[32:35], v[16:31]
	ds_read_b128 v[36:39], v190 offset:13312
	ds_read_b128 v[132:135], v190 offset:13344
	ds_read_b128 v[136:139], v190 offset:13376
	ds_read_b128 v[140:143], v190 offset:13408
	ds_read_b128 v[144:147], v190 offset:13440
	ds_read_b128 v[148:151], v190 offset:13472
	ds_read_b128 v[40:43], v190 offset:19968
	ds_read_b128 v[152:155], v190 offset:20000
	ds_read_b128 v[156:159], v190 offset:20032
	ds_read_b128 v[234:237], v190 offset:20064
	ds_read_b128 v[238:241], v190 offset:20096
	ds_read_b128 v[242:245], v190 offset:20128
	s_waitcnt lgkmcnt(12)
	v_mfma_f32_32x32x16_bf16 v[0:15], v[128:131], v[32:35], v[0:15]
	s_waitcnt lgkmcnt(11)
	v_mfma_f32_32x32x16_bf16 v[48:63], v[36:39], v[64:67], 0
	s_waitcnt lgkmcnt(5)
	v_mfma_f32_32x32x16_bf16 v[32:47], v[40:43], v[64:67], 0
	v_mfma_f32_32x32x16_bf16 v[48:63], v[132:135], v[68:71], v[48:63]
	s_waitcnt lgkmcnt(4)
	v_mfma_f32_32x32x16_bf16 v[32:47], v[152:155], v[68:71], v[32:47]
	v_mfma_f32_32x32x16_bf16 v[48:63], v[136:139], v[72:75], v[48:63]
	s_waitcnt lgkmcnt(3)
	v_mfma_f32_32x32x16_bf16 v[32:47], v[156:159], v[72:75], v[32:47]
	v_mfma_f32_32x32x16_bf16 v[48:63], v[140:143], v[88:91], v[48:63]
	s_waitcnt lgkmcnt(2)
	v_mfma_f32_32x32x16_bf16 v[32:47], v[234:237], v[88:91], v[32:47]
	v_mfma_f32_32x32x16_bf16 v[48:63], v[144:147], v[96:99], v[48:63]
	s_waitcnt lgkmcnt(1)
	v_mfma_f32_32x32x16_bf16 v[32:47], v[238:241], v[96:99], v[32:47]
	v_mfma_f32_32x32x16_bf16 v[48:63], v[148:151], v[100:103], v[48:63]
	s_waitcnt lgkmcnt(0)
	v_mfma_f32_32x32x16_bf16 v[32:47], v[242:245], v[100:103], v[32:47]
	s_nop 3
	ds_read2_b64 v[156:159], v214 offset0:16 offset1:18
	ds_read2_b64 v[148:151], v214 offset0:20 offset1:22
	ds_read2_b64 v[152:155], v215 offset0:48 offset1:50
	ds_read2_b64 v[144:147], v215 offset0:52 offset1:54
	ds_read2_b64 v[140:143], v214 offset0:24 offset1:26
	ds_read2_b64 v[136:139], v215 offset0:56 offset1:58
	ds_read2_b64 v[128:131], v214 offset0:28 offset1:30
	ds_read2_b64 v[132:135], v215 offset0:60 offset1:62
	v_max_f32_e32 v195, v32, v32
	v_max_f32_e32 v200, v48, v48
	v_max_f32_e32 v195, v200, v195
	v_max3_f32 v195, v195, v49, v33
	v_max3_f32 v195, v195, v50, v34
	v_max3_f32 v195, v195, v51, v35
	v_max3_f32 v195, v195, v52, v36
	v_max3_f32 v195, v195, v53, v37
	v_max3_f32 v195, v195, v54, v38
	v_max3_f32 v195, v195, v55, v39
	v_max3_f32 v195, v195, v56, v40
	v_max3_f32 v195, v195, v57, v41
	v_max3_f32 v195, v195, v58, v42
	v_max3_f32 v195, v195, v59, v43
	v_max3_f32 v195, v195, v60, v44
	v_max3_f32 v195, v195, v61, v45
	v_max3_f32 v195, v195, v62, v46
	v_max3_f32 v214, v195, v63, v47
	v_cmp_gt_f32_e32 vcc, v214, v216
	s_cbranch_vccz .LBB0_801
	v_cmp_lt_i32_e32 vcc, v224, v207
	s_nop 1
	v_cndmask_b32_e32 v195, v205, v224, vcc
	v_lshlrev_b32_e32 v195, 2, v195
	ds_bpermute_b32 v195, v195, v214
	s_waitcnt lgkmcnt(0)
	v_max3_f32 v195, v212, v214, v195
	v_sub_f32_e32 v200, v212, v195
	v_exp_f32_e32 v200, v200
	v_mov_b32_e32 v212, v195
	v_mul_f32_e32 v213, v213, v200
	v_pk_mul_f32 v[30:31], v[30:31], v[200:201] op_sel_hi:[1,0]
	v_pk_mul_f32 v[28:29], v[28:29], v[200:201] op_sel_hi:[1,0]
	v_pk_mul_f32 v[26:27], v[26:27], v[200:201] op_sel_hi:[1,0]
	v_pk_mul_f32 v[24:25], v[24:25], v[200:201] op_sel_hi:[1,0]
	v_pk_mul_f32 v[22:23], v[22:23], v[200:201] op_sel_hi:[1,0]
	v_pk_mul_f32 v[20:21], v[20:21], v[200:201] op_sel_hi:[1,0]
	v_pk_mul_f32 v[18:19], v[18:19], v[200:201] op_sel_hi:[1,0]
	v_pk_mul_f32 v[16:17], v[16:17], v[200:201] op_sel_hi:[1,0]
	v_pk_mul_f32 v[14:15], v[14:15], v[200:201] op_sel_hi:[1,0]
	v_pk_mul_f32 v[12:13], v[12:13], v[200:201] op_sel_hi:[1,0]
	v_pk_mul_f32 v[10:11], v[10:11], v[200:201] op_sel_hi:[1,0]
	v_pk_mul_f32 v[8:9], v[8:9], v[200:201] op_sel_hi:[1,0]
	v_pk_mul_f32 v[6:7], v[6:7], v[200:201] op_sel_hi:[1,0]
	v_pk_mul_f32 v[4:5], v[4:5], v[200:201] op_sel_hi:[1,0]
	v_pk_mul_f32 v[2:3], v[2:3], v[200:201] op_sel_hi:[1,0]
	v_pk_mul_f32 v[0:1], v[0:1], v[200:201] op_sel_hi:[1,0]

; #define MFMA(a, b, c) __builtin_amdgcn_mfma_f32_32x32x16_bf16((a), (b), (c), 0, 0, 0)
; DI float fexp2(float x) { return __builtin_amdgcn_exp2f(x); }
; DI f32x16 zero16() { f32x16 z; for (int i = 0; i < 16; ++i) z[i] = 0.f; return z; }
; DI void phase_attn(const Params& p, int hf, bool skipctx, char* smem, int& rot) {
;     ...
;     auto compute = [&](int buf, int half) {
;       const char* sk = smem + buf * STG + half * 64 * KROW; const char* sv = smem + buf * STG + KB_ + half * 128;
;       f32x16 st[2]; st[0] = zero16(); st[1] = zero16();
;       {
;         bf16x8 kf[2][6];
; #pragma unroll
;         for (int kb = 0; kb < 2; ++kb)
; #pragma unroll
;           for (int ks = 0; ks < 6; ++ks) kf[kb][ks] = *(const bf16x8*)(sk + (kb * 32 + r) * KROW + (ks * 16 + h * 8) * 2);
;         __builtin_amdgcn_sched_barrier(0);
; #pragma unroll
;         for (int ks = 0; ks < 6; ++ks)
; #pragma unroll
;           for (int kb = 0; kb < 2; ++kb) st[kb] = MFMA(kf[kb][ks], qf[ks], st[kb]);
;         __builtin_amdgcn_sched_barrier(0);
;       }
;       bf16x8 vf[2][2][2];
; #pragma unroll
;       for (int kb = 0; kb < 2; ++kb)
; #pragma unroll
;         for (int s2 = 0; s2 < 2; ++s2)
; #pragma unroll
;           for (int dvb = 0; dvb < 2; ++dvb) {
;             const char* vp = sv + (dvb * 32 + r) * VROW + (kb * 32 + 16 * s2 + 4 * h) * 2;
;             const s16x4 lo = *(const s16x4*)vp, hi = *(const s16x4*)(vp + 16);
;             vf[kb][s2][dvb] = __builtin_shufflevector(lo, hi, 0, 1, 2, 3, 4, 5, 6, 7);
;           }
;       float mx = st[0][0];
; #pragma unroll
;       for (int i = 0; i < 16; ++i) { mx = fmaxf(mx, st[0][i]); mx = fmaxf(mx, st[1][i]); }
;       if (__any(mx > m_run + 8.f)) {
;         mx = fmaxf(mx, __shfl_xor(mx, 32));
;         const float m_new = fmaxf(m_run, mx);
;         const float alpha = fexp2(m_run - m_new);
;         m_run = m_new;
;         l_run *= alpha;
; #pragma unroll
;         for (int i = 0; i < 16; ++i) { o[0][i] *= alpha; o[1][i] *= alpha; }
;       }
;       float ps = 0.f;
; #pragma unroll
;       for (int kb = 0; kb < 2; ++kb)
; #pragma unroll
;         for (int i = 0; i < 16; ++i) { const float e = fexp2(st[kb][i] - m_run); st[kb][i] = e; ps += e; }
;       l_run += ps;
.LBB0_803:
	v_add_f32_e32 v48, 0, v48
	v_add_f32_e32 v48, v49, v48
	v_add_f32_e32 v48, v50, v48
	v_add_f32_e32 v48, v51, v48
	v_add_f32_e32 v48, v52, v48
	v_add_f32_e32 v48, v53, v48
	v_add_f32_e32 v48, v54, v48
	v_add_f32_e32 v48, v55, v48
	v_add_f32_e32 v48, v56, v48
	v_add_f32_e32 v48, v57, v48
	v_add_f32_e32 v48, v58, v48
	v_add_f32_e32 v48, v59, v48
	v_add_f32_e32 v48, v60, v48
	v_add_f32_e32 v48, v61, v48
	v_add_f32_e32 v48, v62, v48
	v_add_f32_e32 v48, v63, v48
	v_add_f32_e32 v32, v32, v48
	v_add_f32_e32 v32, v33, v32
	v_add_f32_e32 v32, v34, v32
	v_add_f32_e32 v32, v35, v32
	v_add_f32_e32 v32, v36, v32
	v_add_f32_e32 v32, v37, v32
	v_add_f32_e32 v32, v38, v32
	v_add_f32_e32 v32, v39, v32
	v_add_f32_e32 v32, v40, v32
	v_add_f32_e32 v32, v41, v32
	v_add_f32_e32 v32, v42, v32
	v_add_f32_e32 v32, v43, v32
	v_add_f32_e32 v32, v44, v32
	v_add_f32_e32 v32, v45, v32
	v_add_f32_e32 v32, v46, v32
	v_add_f32_e32 v32, v47, v32
	v_add_f32_e32 v213, v213, v32
	ds_read_b128 v[32:35], v190 offset:43520
	ds_read_b128 v[128:131], v190 offset:43552
	ds_read_b128 v[132:135], v190 offset:43584
	ds_read_b128 v[136:139], v190 offset:43616
	ds_read_b128 v[140:143], v190 offset:43648
	ds_read_b128 v[144:147], v190 offset:43680
	ds_read_b128 v[36:39], v190 offset:50176
	ds_read_b128 v[148:151], v190 offset:50208
	ds_read_b128 v[152:155], v190 offset:50240
	ds_read_b128 v[156:159], v190 offset:50272
	ds_read_b128 v[214:217], v190 offset:50304
	ds_read_b128 v[234:237], v190 offset:50336
	s_waitcnt lgkmcnt(11)
	v_mfma_f32_32x32x16_bf16 v[48:63], v[32:35], v[64:67], 0
	s_waitcnt lgkmcnt(5)
	v_mfma_f32_32x32x16_bf16 v[32:47], v[36:39], v[64:67], 0
	v_mfma_f32_32x32x16_bf16 v[48:63], v[128:131], v[68:71], v[48:63]
	s_waitcnt lgkmcnt(4)
	v_mfma_f32_32x32x16_bf16 v[32:47], v[148:151], v[68:71], v[32:47]
	v_mfma_f32_32x32x16_bf16 v[48:63], v[132:135], v[72:75], v[48:63]
	s_waitcnt lgkmcnt(3)
	v_mfma_f32_32x32x16_bf16 v[32:47], v[152:155], v[72:75], v[32:47]
	v_mfma_f32_32x32x16_bf16 v[48:63], v[136:139], v[88:91], v[48:63]
	s_waitcnt lgkmcnt(2)
	v_mfma_f32_32x32x16_bf16 v[32:47], v[156:159], v[88:91], v[32:47]
	v_mfma_f32_32x32x16_bf16 v[48:63], v[140:143], v[96:99], v[48:63]
	s_waitcnt lgkmcnt(1)
	v_mfma_f32_32x32x16_bf16 v[32:47], v[214:217], v[96:99], v[32:47]
	v_mfma_f32_32x32x16_bf16 v[48:63], v[144:147], v[100:103], v[48:63]
	s_waitcnt lgkmcnt(0)
	v_mfma_f32_32x32x16_bf16 v[32:47], v[234:237], v[100:103], v[32:47]
	v_add_u32_e32 v128, 0x2000, v188
	ds_read2_b64 v[152:155], v128 offset0:32 offset1:34
	v_add_u32_e32 v128, v184, v181
	ds_read2_b64 v[156:159], v188 offset1:2
	ds_read2_b64 v[148:151], v128 offset1:2
	ds_read2_b64 v[144:147], v194 offset0:32 offset1:34
	v_add_u32_e32 v128, v184, v182
	ds_read2_b64 v[140:143], v128 offset1:2
	ds_read2_b64 v[136:139], v204 offset0:32 offset1:34
	v_add_u32_e32 v128, v184, v183
	ds_read2_b64 v[132:135], v128 offset1:2
	ds_read2_b64 v[128:131], v206 offset0:32 offset1:34
	v_max_f32_e32 v195, v32, v32
	v_max_f32_e32 v200, v48, v48
	v_max_f32_e32 v195, v200, v195
	v_max3_f32 v195, v195, v49, v33
	v_max3_f32 v195, v195, v50, v34
	v_max3_f32 v195, v195, v51, v35
	v_max3_f32 v195, v195, v52, v36
	v_max3_f32 v195, v195, v53, v37
	v_max3_f32 v195, v195, v54, v38
	v_max3_f32 v195, v195, v55, v39
	v_max3_f32 v195, v195, v56, v40
	v_max3_f32 v195, v195, v57, v41
	v_max3_f32 v195, v195, v58, v42
	v_max3_f32 v195, v195, v59, v43
	v_max3_f32 v195, v195, v60, v44
	v_max3_f32 v195, v195, v61, v45
	v_max3_f32 v195, v195, v62, v46
	v_max3_f32 v215, v195, v63, v47
	v_add_f32_e32 v214, 0x41000000, v212
	v_cmp_gt_f32_e32 vcc, v215, v214
	s_cbranch_vccz .LBB0_805
	v_cmp_lt_i32_e32 vcc, v224, v207
	s_nop 1
	v_cndmask_b32_e32 v195, v205, v224, vcc
	v_lshlrev_b32_e32 v195, 2, v195
	ds_bpermute_b32 v195, v195, v215
	s_waitcnt lgkmcnt(0)
	v_max3_f32 v195, v212, v215, v195
	v_sub_f32_e32 v200, v212, v195
	v_exp_f32_e32 v200, v200
	v_add_f32_e32 v214, 0x41000000, v195
	v_mov_b32_e32 v212, v195
	v_mul_f32_e32 v213, v213, v200
	v_pk_mul_f32 v[30:31], v[30:31], v[200:201] op_sel_hi:[1,0]
	v_pk_mul_f32 v[28:29], v[28:29], v[200:201] op_sel_hi:[1,0]
	v_pk_mul_f32 v[26:27], v[26:27], v[200:201] op_sel_hi:[1,0]
	v_pk_mul_f32 v[24:25], v[24:25], v[200:201] op_sel_hi:[1,0]
	v_pk_mul_f32 v[22:23], v[22:23], v[200:201] op_sel_hi:[1,0]
	v_pk_mul_f32 v[20:21], v[20:21], v[200:201] op_sel_hi:[1,0]
	v_pk_mul_f32 v[18:19], v[18:19], v[200:201] op_sel_hi:[1,0]
	v_pk_mul_f32 v[16:17], v[16:17], v[200:201] op_sel_hi:[1,0]
	v_pk_mul_f32 v[14:15], v[14:15], v[200:201] op_sel_hi:[1,0]
	v_pk_mul_f32 v[12:13], v[12:13], v[200:201] op_sel_hi:[1,0]
	v_pk_mul_f32 v[10:11], v[10:11], v[200:201] op_sel_hi:[1,0]
	v_pk_mul_f32 v[8:9], v[8:9], v[200:201] op_sel_hi:[1,0]
	v_pk_mul_f32 v[6:7], v[6:7], v[200:201] op_sel_hi:[1,0]
	v_pk_mul_f32 v[4:5], v[4:5], v[200:201] op_sel_hi:[1,0]
	v_pk_mul_f32 v[2:3], v[2:3], v[200:201] op_sel_hi:[1,0]
	v_pk_mul_f32 v[0:1], v[0:1], v[200:201] op_sel_hi:[1,0]
; DI float fexp2(float x) { return __builtin_amdgcn_exp2f(x); }
; DI void phase_attn(const Params& p, int hf, bool skipctx, char* smem, int& rot) {
;     ...
;     auto compute = [&](int buf, int half) {
;       const char* sk = smem + buf * STG + half * 64 * KROW; const char* sv = smem + buf * STG + KB_ + half * 128;
;       f32x16 st[2]; st[0] = zero16(); st[1] = zero16();
;       {
;         bf16x8 kf[2][6];
; #pragma unroll
;         for (int kb = 0; kb < 2; ++kb)
; #pragma unroll
;           for (int ks = 0; ks < 6; ++ks) kf[kb][ks] = *(const bf16x8*)(sk + (kb * 32 + r) * KROW + (ks * 16 + h * 8) * 2);
;         __builtin_amdgcn_sched_barrier(0);
; #pragma unroll
;         for (int ks = 0; ks < 6; ++ks)
; #pragma unroll
;           for (int kb = 0; kb < 2; ++kb) st[kb] = MFMA(kf[kb][ks], qf[ks], st[kb]);
;         __builtin_amdgcn_sched_barrier(0);
;       }
;       bf16x8 vf[2][2][2];
; #pragma unroll
;       for (int kb = 0; kb < 2; ++kb)
; #pragma unroll
;         for (int s2 = 0; s2 < 2; ++s2)
; #pragma unroll
;           for (int dvb = 0; dvb < 2; ++dvb) {
;             const char* vp = sv + (dvb * 32 + r) * VROW + (kb * 32 + 16 * s2 + 4 * h) * 2;
;             const s16x4 lo = *(const s16x4*)vp, hi = *(const s16x4*)(vp + 16);
;             vf[kb][s2][dvb] = __builtin_shufflevector(lo, hi, 0, 1, 2, 3, 4, 5, 6, 7);
;           }
;       float mx = st[0][0];
; #pragma unroll
;       for (int i = 0; i < 16; ++i) { mx = fmaxf(mx, st[0][i]); mx = fmaxf(mx, st[1][i]); }
;       if (__any(mx > m_run + 8.f)) {
;         mx = fmaxf(mx, __shfl_xor(mx, 32));
;         const float m_new = fmaxf(m_run, mx);
;         const float alpha = fexp2(m_run - m_new);
;         m_run = m_new;
;         l_run *= alpha;
; #pragma unroll
;         for (int i = 0; i < 16; ++i) { o[0][i] *= alpha; o[1][i] *= alpha; }
;       }
;       float ps = 0.f;
; #pragma unroll
;       for (int kb = 0; kb < 2; ++kb)
; #pragma unroll
;         for (int i = 0; i < 16; ++i) { const float e = fexp2(st[kb][i] - m_run); st[kb][i] = e; ps += e; }
;       l_run += ps;
; #pragma unroll
;       for (int kb = 0; kb < 2; ++kb)
; #pragma unroll
;         for (int s2 = 0; s2 < 2; ++s2) {
;           const bf16x8 pb = pack8(st[kb][8 * s2 + 0], st[kb][8 * s2 + 1], st[kb][8 * s2 + 2], st[kb][8 * s2 + 3], st[kb][8 * s2 + 4], st[kb][8 * s2 + 5], st[kb][8 * s2 + 6], st[kb][8 * s2 + 7]);
; #pragma unroll
.LBB0_805:
	v_sub_f32_e32 v48, v48, v212
	v_exp_f32_e32 v48, v48
	v_sub_f32_e32 v49, v49, v212
	v_exp_f32_e32 v49, v49
	v_sub_f32_e32 v50, v50, v212
	v_exp_f32_e32 v50, v50
	v_sub_f32_e32 v51, v51, v212
	v_exp_f32_e32 v51, v51
	v_sub_f32_e32 v52, v52, v212
	v_add_f32_e32 v195, 0, v48
	v_exp_f32_e32 v52, v52
	v_sub_f32_e32 v53, v53, v212
	v_add_f32_e32 v195, v49, v195
	v_exp_f32_e32 v53, v53
	v_sub_f32_e32 v54, v54, v212
	v_add_f32_e32 v195, v50, v195
	v_exp_f32_e32 v54, v54
	v_sub_f32_e32 v55, v55, v212
	v_add_f32_e32 v195, v51, v195
	v_exp_f32_e32 v55, v55
	v_sub_f32_e32 v56, v56, v212
	v_add_f32_e32 v195, v52, v195
	v_exp_f32_e32 v56, v56
	v_sub_f32_e32 v57, v57, v212
	v_add_f32_e32 v195, v53, v195
	v_exp_f32_e32 v57, v57
	v_sub_f32_e32 v58, v58, v212
	v_add_f32_e32 v195, v54, v195
	v_exp_f32_e32 v58, v58
	v_sub_f32_e32 v59, v59, v212
	v_add_f32_e32 v195, v55, v195
	v_exp_f32_e32 v59, v59
	v_sub_f32_e32 v60, v60, v212
	v_add_f32_e32 v195, v56, v195
	v_exp_f32_e32 v60, v60
	v_sub_f32_e32 v61, v61, v212
	v_add_f32_e32 v195, v57, v195
	v_exp_f32_e32 v61, v61
	v_sub_f32_e32 v62, v62, v212
	v_add_f32_e32 v195, v58, v195
	v_exp_f32_e32 v62, v62
	v_sub_f32_e32 v63, v63, v212
	v_add_f32_e32 v195, v59, v195
	v_exp_f32_e32 v63, v63
	v_sub_f32_e32 v32, v32, v212
	v_add_f32_e32 v195, v60, v195
	v_exp_f32_e32 v200, v32
	v_sub_f32_e32 v32, v33, v212
	v_add_f32_e32 v195, v61, v195
	v_exp_f32_e32 v201, v32
	v_sub_f32_e32 v33, v34, v212
	v_add_f32_e32 v32, v62, v195
	v_exp_f32_e32 v195, v33
	v_sub_f32_e32 v33, v35, v212
	v_add_f32_e32 v32, v63, v32
	v_exp_f32_e32 v202, v33
	v_sub_f32_e32 v33, v36, v212
	v_add_f32_e32 v32, v200, v32
	v_exp_f32_e32 v36, v33
	v_sub_f32_e32 v33, v37, v212
	v_add_f32_e32 v32, v201, v32
	v_exp_f32_e32 v37, v33
	v_add_f32_e32 v32, v195, v32
	v_add_f32_e32 v32, v202, v32
	v_add_f32_e32 v32, v36, v32
	v_add_f32_e32 v203, v37, v32
	v_cvt_pk_bf16_f32 v32, v48, v49
	v_cvt_pk_bf16_f32 v33, v50, v51
	v_cvt_pk_bf16_f32 v34, v52, v53
	v_cvt_pk_bf16_f32 v35, v54, v55
	v_sub_f32_e32 v38, v38, v212
	v_exp_f32_e32 v38, v38
	s_waitcnt lgkmcnt(6)
	v_mfma_f32_32x32x16_bf16 v[16:31], v[156:159], v[32:35], v[16:31]
	v_sub_f32_e32 v39, v39, v212
	v_exp_f32_e32 v39, v39
	v_sub_f32_e32 v40, v40, v212
	v_exp_f32_e32 v40, v40
	v_sub_f32_e32 v42, v42, v212
	v_add_f32_e32 v48, v38, v203
	v_exp_f32_e32 v42, v42
	v_mfma_f32_32x32x16_bf16 v[0:15], v[152:155], v[32:35], v[0:15]
	v_sub_f32_e32 v32, v41, v212
	v_exp_f32_e32 v41, v32
	v_cvt_pk_bf16_f32 v32, v56, v57
	v_cvt_pk_bf16_f32 v33, v58, v59
	v_cvt_pk_bf16_f32 v34, v60, v61
	v_cvt_pk_bf16_f32 v35, v62, v63
	v_sub_f32_e32 v43, v43, v212
	v_add_f32_e32 v48, v39, v48
	s_waitcnt lgkmcnt(5)
	v_mfma_f32_32x32x16_bf16 v[16:31], v[148:151], v[32:35], v[16:31]
	v_exp_f32_e32 v43, v43
	v_sub_f32_e32 v44, v44, v212
	v_add_f32_e32 v48, v40, v48
	v_exp_f32_e32 v44, v44
	v_add_f32_e32 v48, v41, v48
	s_waitcnt lgkmcnt(4)
	v_mfma_f32_32x32x16_bf16 v[0:15], v[144:147], v[32:35], v[0:15]
	v_add_f32_e32 v32, v42, v48
	v_add_f32_e32 v32, v43, v32
	v_add_f32_e32 v48, v44, v32
	v_cvt_pk_bf16_f32 v32, v200, v201
	v_cvt_pk_bf16_f32 v33, v195, v202
	v_cvt_pk_bf16_f32 v34, v36, v37
	v_cvt_pk_bf16_f32 v35, v38, v39
	v_sub_f32_e32 v36, v45, v212
	v_exp_f32_e32 v36, v36
	s_waitcnt lgkmcnt(3)
	v_mfma_f32_32x32x16_bf16 v[16:31], v[140:143], v[32:35], v[16:31]
	v_sub_f32_e32 v37, v46, v212
	v_exp_f32_e32 v37, v37
	v_sub_f32_e32 v38, v47, v212
	v_exp_f32_e32 v38, v38
	v_add_f32_e32 v39, v36, v48
	s_waitcnt lgkmcnt(2)
	v_mfma_f32_32x32x16_bf16 v[0:15], v[136:139], v[32:35], v[0:15]
	v_add_f32_e32 v32, v37, v39
	v_add_f32_e32 v32, v38, v32
	v_add_f32_e32 v213, v213, v32
	v_cvt_pk_bf16_f32 v32, v40, v41
	v_cvt_pk_bf16_f32 v33, v42, v43
	v_cvt_pk_bf16_f32 v34, v44, v36
	v_cvt_pk_bf16_f32 v35, v37, v38
	s_waitcnt lgkmcnt(1)
	s_nop 0
	v_mfma_f32_32x32x16_bf16 v[16:31], v[132:135], v[32:35], v[16:31]
	ds_read_b128 v[36:39], v190 offset:56832
	ds_read_b128 v[132:135], v190 offset:56864
	ds_read_b128 v[136:139], v190 offset:56896
	ds_read_b128 v[140:143], v190 offset:56928
	ds_read_b128 v[144:147], v190 offset:56960
	ds_read_b128 v[148:151], v190 offset:56992
	ds_read_b128 v[40:43], v190 offset:63488
	ds_read_b128 v[152:155], v190 offset:63520
	ds_read_b128 v[156:159], v190 offset:63552
	ds_read_b128 v[216:219], v190 offset:63584
	ds_read_b128 v[234:237], v190 offset:63616
	ds_read_b128 v[238:241], v190 offset:63648
	s_waitcnt lgkmcnt(12)
	v_mfma_f32_32x32x16_bf16 v[0:15], v[128:131], v[32:35], v[0:15]
	s_waitcnt lgkmcnt(11)
	v_mfma_f32_32x32x16_bf16 v[48:63], v[36:39], v[64:67], 0
	s_waitcnt lgkmcnt(5)
	v_mfma_f32_32x32x16_bf16 v[32:47], v[40:43], v[64:67], 0
	v_mfma_f32_32x32x16_bf16 v[48:63], v[132:135], v[68:71], v[48:63]
	s_waitcnt lgkmcnt(4)
	v_mfma_f32_32x32x16_bf16 v[32:47], v[152:155], v[68:71], v[32:47]
	v_mfma_f32_32x32x16_bf16 v[48:63], v[136:139], v[72:75], v[48:63]
	s_waitcnt lgkmcnt(3)
	v_mfma_f32_32x32x16_bf16 v[32:47], v[156:159], v[72:75], v[32:47]
	v_mfma_f32_32x32x16_bf16 v[48:63], v[140:143], v[88:91], v[48:63]
	s_waitcnt lgkmcnt(2)
	v_mfma_f32_32x32x16_bf16 v[32:47], v[216:219], v[88:91], v[32:47]
	v_mfma_f32_32x32x16_bf16 v[48:63], v[144:147], v[96:99], v[48:63]
	s_waitcnt lgkmcnt(1)
	v_mfma_f32_32x32x16_bf16 v[32:47], v[234:237], v[96:99], v[32:47]
	v_mfma_f32_32x32x16_bf16 v[48:63], v[148:151], v[100:103], v[48:63]
	s_waitcnt lgkmcnt(0)
	v_mfma_f32_32x32x16_bf16 v[32:47], v[238:241], v[100:103], v[32:47]
	v_add_u32_e32 v128, 0x2000, v189
	ds_read2_b64 v[152:155], v128 offset0:32 offset1:34
	v_add_u32_e32 v128, v185, v181
	ds_read2_b64 v[156:159], v189 offset1:2
	ds_read2_b64 v[148:151], v128 offset1:2
	ds_read2_b64 v[144:147], v208 offset0:32 offset1:34
	v_add_u32_e32 v128, v185, v182
	ds_read2_b64 v[140:143], v128 offset1:2
	ds_read2_b64 v[136:139], v210 offset0:32 offset1:34
	v_add_u32_e32 v128, v185, v183
	ds_read2_b64 v[132:135], v128 offset1:2
	ds_read2_b64 v[128:131], v211 offset0:32 offset1:34
	v_max_f32_e32 v195, v32, v32
	v_max_f32_e32 v200, v48, v48
	v_max_f32_e32 v195, v200, v195
	v_max3_f32 v195, v195, v49, v33
	v_max3_f32 v195, v195, v50, v34
	v_max3_f32 v195, v195, v51, v35
	v_max3_f32 v195, v195, v52, v36
	v_max3_f32 v195, v195, v53, v37
	v_max3_f32 v195, v195, v54, v38
	v_max3_f32 v195, v195, v55, v39
	v_max3_f32 v195, v195, v56, v40
	v_max3_f32 v195, v195, v57, v41
	v_max3_f32 v195, v195, v58, v42
	v_max3_f32 v195, v195, v59, v43
	v_max3_f32 v195, v195, v60, v44
	v_max3_f32 v195, v195, v61, v45
	v_max3_f32 v195, v195, v62, v46
	v_max3_f32 v215, v195, v63, v47
	v_cmp_gt_f32_e32 vcc, v215, v214
	s_cbranch_vccz .LBB0_807
; DI float fexp2(float x) { return __builtin_amdgcn_exp2f(x); }
; DI void phase_attn(const Params& p, int hf, bool skipctx, char* smem, int& rot) {
;     ...
;       if (__any(mx > m_run + 8.f)) {
;         mx = fmaxf(mx, __shfl_xor(mx, 32));
;         const float m_new = fmaxf(m_run, mx);
;         const float alpha = fexp2(m_run - m_new);
;         m_run = m_new;
;         l_run *= alpha;
; #pragma unroll
;         for (int i = 0; i < 16; ++i) { o[0][i] *= alpha; o[1][i] *= alpha; }
;       }
	v_cmp_lt_i32_e32 vcc, v224, v207
	s_nop 1
	v_cndmask_b32_e32 v195, v205, v224, vcc
	v_lshlrev_b32_e32 v195, 2, v195
	ds_bpermute_b32 v195, v195, v215
	s_waitcnt lgkmcnt(0)
	v_max3_f32 v195, v212, v215, v195
	v_sub_f32_e32 v200, v212, v195
	v_exp_f32_e32 v200, v200
	v_mov_b32_e32 v212, v195
	v_mul_f32_e32 v213, v213, v200
	v_pk_mul_f32 v[30:31], v[30:31], v[200:201] op_sel_hi:[1,0]
	v_pk_mul_f32 v[28:29], v[28:29], v[200:201] op_sel_hi:[1,0]
	v_pk_mul_f32 v[26:27], v[26:27], v[200:201] op_sel_hi:[1,0]
	v_pk_mul_f32 v[24:25], v[24:25], v[200:201] op_sel_hi:[1,0]
	v_pk_mul_f32 v[22:23], v[22:23], v[200:201] op_sel_hi:[1,0]
	v_pk_mul_f32 v[20:21], v[20:21], v[200:201] op_sel_hi:[1,0]
	v_pk_mul_f32 v[18:19], v[18:19], v[200:201] op_sel_hi:[1,0]
	v_pk_mul_f32 v[16:17], v[16:17], v[200:201] op_sel_hi:[1,0]
	v_pk_mul_f32 v[14:15], v[14:15], v[200:201] op_sel_hi:[1,0]
	v_pk_mul_f32 v[12:13], v[12:13], v[200:201] op_sel_hi:[1,0]
	v_pk_mul_f32 v[10:11], v[10:11], v[200:201] op_sel_hi:[1,0]
	v_pk_mul_f32 v[8:9], v[8:9], v[200:201] op_sel_hi:[1,0]
	v_pk_mul_f32 v[6:7], v[6:7], v[200:201] op_sel_hi:[1,0]
	v_pk_mul_f32 v[4:5], v[4:5], v[200:201] op_sel_hi:[1,0]
	v_pk_mul_f32 v[2:3], v[2:3], v[200:201] op_sel_hi:[1,0]
	v_pk_mul_f32 v[0:1], v[0:1], v[200:201] op_sel_hi:[1,0]
